# attention PV: V-fragment LDS address adds folded into ds_read_b64 16-bit offsets (8 VALU fewer per k-iteration)
# baseline (speedup 1.0000x reference)
.Lmy_at_s1:
	v_exp_f32_e32 v170, v116
	v_fma_f32 v116, v178, s27, -v160
	v_add3_u32 v139, s10, v115, v114
	v_add3_u32 v190, s10, v152, v114
	v_fma_f32 v128, v182, s27, -v160
	v_fma_f32 v130, v183, s27, -v160
	v_fma_f32 v132, v184, s27, -v160
	v_fma_f32 v134, v185, s27, -v160
	ds_read_b64 v[174:175], v139 offset:17408
	ds_read_b64 v[176:177], v139 offset:17440
	ds_read_b64 v[182:183], v190 offset:17408
	ds_read_b64 v[184:185], v190 offset:17440
	v_exp_f32_e32 v171, v116
	v_fma_f32 v116, v179, s27, -v160
	v_exp_f32_e32 v172, v116
	v_fma_f32 v116, v180, s27, -v160
	v_fma_f32 v118, v181, s27, -v160
	v_exp_f32_e32 v116, v116
	v_exp_f32_e32 v118, v118
	v_cvt_pk_bf16_f32 v143, v117, v119
	v_cvt_pk_bf16_f32 v142, v165, v166
	v_cvt_pk_bf16_f32 v141, v163, v164
	v_cvt_pk_bf16_f32 v140, v161, v162
	v_cvt_pk_bf16_f32 v181, v116, v118
	v_cvt_pk_bf16_f32 v180, v171, v172
	v_cvt_pk_bf16_f32 v179, v169, v170
	v_cvt_pk_bf16_f32 v178, v167, v168
	s_waitcnt lgkmcnt(2)
	v_mfma_f32_16x16x32_bf16 v[96:99], v[174:177], v[140:143], v[96:99]
	v_mfma_f32_16x16x32_bf16 v[80:83], v[174:177], v[178:181], v[80:83]
	v_add3_u32 v191, s10, v153, v114
	ds_read_b64 v[174:175], v191 offset:17408
	ds_read_b64 v[176:177], v191 offset:17440
	s_waitcnt lgkmcnt(2)
	v_mfma_f32_16x16x32_bf16 v[92:95], v[182:185], v[140:143], v[92:95]
	v_mfma_f32_16x16x32_bf16 v[68:71], v[182:185], v[178:181], v[68:71]
	v_add3_u32 v192, s10, v154, v114
	ds_read_b64 v[182:183], v192 offset:17408
	ds_read_b64 v[184:185], v192 offset:17440
	s_waitcnt lgkmcnt(2)
	v_mfma_f32_16x16x32_bf16 v[76:79], v[174:177], v[140:143], v[76:79]
	v_mfma_f32_16x16x32_bf16 v[56:59], v[174:177], v[178:181], v[56:59]
	ds_read_b64 v[174:175], v139 offset:26624
	ds_read_b64 v[176:177], v139 offset:26656
	s_waitcnt lgkmcnt(2)
	v_mfma_f32_16x16x32_bf16 v[72:75], v[182:185], v[140:143], v[72:75]
	v_mfma_f32_16x16x32_bf16 v[24:27], v[182:185], v[178:181], v[24:27]
	ds_read_b64 v[182:183], v139 offset:28928
	ds_read_b64 v[184:185], v139 offset:28960
	s_waitcnt lgkmcnt(2)
	v_mfma_f32_16x16x32_bf16 v[60:63], v[174:177], v[140:143], v[60:63]
	v_mfma_f32_16x16x32_bf16 v[64:67], v[174:177], v[178:181], v[64:67]
	ds_read_b64 v[174:175], v139 offset:31232
	ds_read_b64 v[176:177], v139 offset:31264
	v_fma_f32 v120, v186, s27, -v160
	s_waitcnt lgkmcnt(2)
	v_mfma_f32_16x16x32_bf16 v[28:31], v[182:185], v[140:143], v[28:31]
	v_fma_f32 v122, v187, s27, -v160
	v_fma_f32 v124, v188, s27, -v160
	v_fma_f32 v126, v189, s27, -v160
	v_mfma_f32_16x16x32_bf16 v[44:47], v[182:185], v[178:181], v[44:47]
	ds_read_b64 v[182:183], v139 offset:33536
	ds_read_b64 v[184:185], v139 offset:33568
	ds_read_b64 v[196:197], v190 offset:17472
	ds_read_b64 v[198:199], v190 offset:17504
	ds_read_b64 v[200:201], v139 offset:17472
	ds_read_b64 v[202:203], v139 offset:17504
	ds_read_b64 v[204:205], v191 offset:17472
	ds_read_b64 v[206:207], v191 offset:17504
	ds_read_b64 v[208:209], v192 offset:17472
	ds_read_b64 v[210:211], v192 offset:17504
	ds_read_b64 v[212:213], v139 offset:26688
	ds_read_b64 v[214:215], v139 offset:26720
	ds_read_b64 v[216:217], v139 offset:28992
	ds_read_b64 v[218:219], v139 offset:29024
	ds_read_b64 v[220:221], v139 offset:31296
	ds_read_b64 v[222:223], v139 offset:31328
	ds_read_b64 v[226:227], v139 offset:33600
	ds_read_b64 v[228:229], v139 offset:33632
	v_exp_f32_e32 v120, v120
	v_exp_f32_e32 v122, v122
	s_waitcnt lgkmcnt(15)
	v_mfma_f32_16x16x32_bf16 v[32:35], v[174:177], v[178:181], v[32:35]
	v_exp_f32_e32 v124, v124
	v_exp_f32_e32 v126, v126
	v_exp_f32_e32 v128, v128
	s_waitcnt lgkmcnt(15)
	v_mfma_f32_16x16x32_bf16 v[88:91], v[182:185], v[178:181], v[88:91]
	v_exp_f32_e32 v130, v130
	v_exp_f32_e32 v132, v132
	v_exp_f32_e32 v134, v134
	v_mfma_f32_16x16x32_bf16 v[20:23], v[174:177], v[140:143], v[20:23]
	v_cvt_pk_bf16_f32 v177, v133, v135
	v_cvt_pk_bf16_f32 v176, v129, v131
	v_cvt_pk_bf16_f32 v175, v125, v127
	v_mfma_f32_16x16x32_bf16 v[84:87], v[182:185], v[140:143], v[84:87]
	v_cvt_pk_bf16_f32 v174, v121, v123
	v_cvt_pk_bf16_f32 v143, v132, v134
	v_cvt_pk_bf16_f32 v142, v128, v130
	v_cvt_pk_bf16_f32 v141, v124, v126
	v_cvt_pk_bf16_f32 v140, v120, v122
	s_waitcnt lgkmcnt(14)
	v_mfma_f32_16x16x32_bf16 v[92:95], v[196:199], v[174:177], v[92:95]
	v_mfma_f32_16x16x32_bf16 v[68:71], v[196:199], v[140:143], v[68:71]
	s_waitcnt lgkmcnt(10)
	v_mfma_f32_16x16x32_bf16 v[76:79], v[204:207], v[174:177], v[76:79]
	v_mfma_f32_16x16x32_bf16 v[56:59], v[204:207], v[140:143], v[56:59]
	s_waitcnt lgkmcnt(8)
	v_mfma_f32_16x16x32_bf16 v[72:75], v[208:211], v[174:177], v[72:75]
	v_mfma_f32_16x16x32_bf16 v[24:27], v[208:211], v[140:143], v[24:27]
	s_waitcnt lgkmcnt(6)
	v_mfma_f32_16x16x32_bf16 v[60:63], v[212:215], v[174:177], v[60:63]
	v_mfma_f32_16x16x32_bf16 v[64:67], v[212:215], v[140:143], v[64:67]
	s_waitcnt lgkmcnt(4)
	v_mfma_f32_16x16x32_bf16 v[28:31], v[216:219], v[174:177], v[28:31]
	v_mfma_f32_16x16x32_bf16 v[44:47], v[216:219], v[140:143], v[44:47]
	s_waitcnt lgkmcnt(2)
	v_mfma_f32_16x16x32_bf16 v[20:23], v[220:223], v[174:177], v[20:23]
	v_mfma_f32_16x16x32_bf16 v[32:35], v[220:223], v[140:143], v[32:35]
	v_mfma_f32_16x16x32_bf16 v[96:99], v[200:203], v[174:177], v[96:99]
	v_mfma_f32_16x16x32_bf16 v[80:83], v[200:203], v[140:143], v[80:83]
	s_waitcnt lgkmcnt(0)
	v_mfma_f32_16x16x32_bf16 v[84:87], v[226:229], v[174:177], v[84:87]
	v_mfma_f32_16x16x32_bf16 v[88:91], v[226:229], v[140:143], v[88:91]
	s_and_saveexec_b64 s[10:11], s[6:7]
	s_cbranch_execz .LBB0_717
	s_cmp_eq_u32 s13, 1
	s_cselect_b32 s6, 0x8c00, 0
	s_add_i32 s6, s6, 16
	v_add3_u32 v139, s6, v155, v102
	s_waitcnt vmcnt(0)
	ds_write_b128 v139, v[4:7]
	ds_write_b128 v139, v[8:11] offset:8704
	v_add3_u32 v139, s6, v156, v104
	ds_write_b128 v139, v[12:15] offset:17408
	ds_write_b128 v139, v[16:19] offset:26624
	s_branch .LBB0_717
